# v26: v25 + nt cache policy on the 8 read-once w_ada f32 loads of the P0 modulation loop
# baseline (speedup 1.0000x reference)
; __device__ __forceinline__ void p0_mod_item(LAS unsigned char* lds, int item, const float* w_ada, const float* b_ada, float* MOD, int tid) {
;     ...
; #pragma unroll 1
;     for (int k0 = 0; k0 < 128; k0 += 32) {
;         f32x4 wv[8];
; #pragma unroll
;         for (int i = 0; i < 8; ++i) wv[i] = *(const f32x4*)(W + (size_t)(wave * 128 + k0 + i * 4 + kr) * 6144);
; #pragma unroll
;         for (int i = 0; i < 8; ++i) { const int k = wave * 128 + k0 + i * 4 + kr;
; #pragma unroll
;             for (int r = 0; r < 9; ++r) acc[r] = acc[r] + wv[i] * sl[r * 1024 + k]; }
.LBB0_14:
	v_add_u32_e32 v59, s10, v84
	v_add_u32_e32 v57, 0x1000, v56
	v_add_u32_e32 v58, 0x2000, v56
	v_add_u32_e32 v62, 0x5000, v56
	v_add_u32_e32 v63, 0x6000, v56
	v_add_u32_e32 v66, 32, v59
	v_add_u32_e32 v67, 36, v59
	v_add_u32_e32 v68, 40, v59
	v_add_u32_e32 v69, 44, v59
	v_add_u32_e32 v72, 48, v59
	v_add_u32_e32 v73, 52, v59
	v_add_u32_e32 v76, 56, v59
	v_add_u32_e32 v77, 60, v59
	ds_read2_b32 v[50:51], v56 offset1:4
	ds_read2_b32 v[48:49], v56 offset0:8 offset1:12
	v_add_u32_e32 v60, 0x3000, v56
	v_add_u32_e32 v61, 0x4000, v56
	v_add_u32_e32 v64, 0x7000, v56
	v_add_u32_e32 v65, 0x8000, v56
	ds_read2_b32 v[52:53], v56 offset0:16 offset1:20
	ds_read2_b32 v[54:55], v56 offset0:24 offset1:28
	ds_read2_b32 v[94:95], v57 offset1:4
	ds_read2_b32 v[96:97], v58 offset1:4
	ds_read2_b32 v[98:99], v60 offset1:4
	ds_read2_b32 v[100:101], v61 offset1:4
	ds_read2_b32 v[102:103], v62 offset1:4
	ds_read2_b32 v[104:105], v63 offset1:4
	ds_read2_b32 v[106:107], v64 offset1:4
	ds_read2_b32 v[108:109], v65 offset1:4
	ds_read2_b32 v[110:111], v57 offset0:8 offset1:12
	ds_read2_b32 v[112:113], v58 offset0:8 offset1:12
	ds_read2_b32 v[114:115], v60 offset0:8 offset1:12
	ds_read2_b32 v[116:117], v61 offset0:8 offset1:12
	ds_read2_b32 v[118:119], v62 offset0:8 offset1:12
	ds_read2_b32 v[120:121], v63 offset0:8 offset1:12
	ds_read2_b32 v[122:123], v64 offset0:8 offset1:12
	ds_read2_b32 v[124:125], v65 offset0:8 offset1:12
	ds_read2_b32 v[126:127], v57 offset0:16 offset1:20
	ds_read2_b32 v[128:129], v58 offset0:16 offset1:20
	ds_read2_b32 v[130:131], v60 offset0:16 offset1:20
	ds_read2_b32 v[132:133], v61 offset0:16 offset1:20
	ds_read2_b32 v[134:135], v62 offset0:16 offset1:20
	ds_read2_b32 v[136:137], v63 offset0:16 offset1:20
	ds_read2_b32 v[138:139], v64 offset0:16 offset1:20
	ds_read2_b32 v[140:141], v65 offset0:16 offset1:20
	ds_read2_b32 v[142:143], v57 offset0:24 offset1:28
	ds_read2_b32 v[144:145], v58 offset0:24 offset1:28
	ds_read2_b32 v[146:147], v60 offset0:24 offset1:28
	ds_read2_b32 v[148:149], v61 offset0:24 offset1:28
	ds_read2_b32 v[150:151], v62 offset0:24 offset1:28
	ds_read2_b32 v[152:153], v63 offset0:24 offset1:28
	ds_read2_b32 v[154:155], v64 offset0:24 offset1:28
	ds_read2_b32 v[156:157], v65 offset0:24 offset1:28
	v_mad_i64_i32 v[58:59], s[18:19], v66, s14, v[20:21]
	v_mad_i64_i32 v[62:63], s[18:19], v67, s14, v[20:21]
	v_mad_i64_i32 v[66:67], s[18:19], v68, s14, v[20:21]
	v_mad_i64_i32 v[70:71], s[18:19], v69, s14, v[20:21]
	v_mad_i64_i32 v[74:75], s[18:19], v72, s14, v[20:21]
	v_mad_i64_i32 v[78:79], s[18:19], v73, s14, v[20:21]
	v_mad_i64_i32 v[86:87], s[18:19], v76, s14, v[20:21]
	v_mad_i64_i32 v[90:91], s[18:19], v77, s14, v[20:21]
	global_load_dwordx4 v[58:61], v[58:59], off nt
	s_nop 0
	global_load_dwordx4 v[62:65], v[62:63], off nt
	s_nop 0
	global_load_dwordx4 v[66:69], v[66:67], off nt
	s_nop 0
	global_load_dwordx4 v[70:73], v[70:71], off nt
	s_nop 0
	global_load_dwordx4 v[74:77], v[74:75], off nt
	s_nop 0
	global_load_dwordx4 v[78:81], v[78:79], off nt
	s_nop 0
	global_load_dwordx4 v[86:89], v[86:87], off nt
	s_nop 0
	global_load_dwordx4 v[90:93], v[90:91], off nt
	s_waitcnt lgkmcnt(14)
	v_mov_b32_e32 v158, v51
	v_mov_b32_e32 v166, v95
	v_mov_b32_e32 v168, v97
	v_mov_b32_e32 v170, v99
	v_mov_b32_e32 v172, v101
	v_mov_b32_e32 v174, v103
	v_mov_b32_e32 v176, v105
	v_mov_b32_e32 v178, v107
	v_mov_b32_e32 v180, v109
	v_mov_b32_e32 v160, v49
	v_mov_b32_e32 v182, v111
	v_mov_b32_e32 v184, v113
	v_mov_b32_e32 v186, v115
	v_mov_b32_e32 v188, v117
	v_mov_b32_e32 v190, v119
	v_mov_b32_e32 v192, v121
	v_mov_b32_e32 v194, v123
	v_mov_b32_e32 v196, v125
	v_mov_b32_e32 v162, v53
	v_mov_b32_e32 v198, v127
	v_mov_b32_e32 v200, v129
	s_waitcnt lgkmcnt(13)
	v_mov_b32_e32 v202, v131
	s_waitcnt lgkmcnt(12)
	v_mov_b32_e32 v204, v133
	s_waitcnt lgkmcnt(11)
	v_mov_b32_e32 v206, v135
	s_waitcnt lgkmcnt(10)
	v_mov_b32_e32 v208, v137
	s_waitcnt lgkmcnt(9)
	v_mov_b32_e32 v210, v139
	s_waitcnt lgkmcnt(8)
	v_mov_b32_e32 v212, v141
	s_add_i32 s10, s10, 32
	v_mov_b32_e32 v164, v55
	s_waitcnt lgkmcnt(7)
	v_mov_b32_e32 v214, v143
	s_waitcnt lgkmcnt(6)
	v_mov_b32_e32 v216, v145
	s_waitcnt lgkmcnt(5)
	v_mov_b32_e32 v218, v147
	s_waitcnt lgkmcnt(4)
	v_mov_b32_e32 v220, v149
	s_waitcnt lgkmcnt(3)
	v_mov_b32_e32 v222, v151
	s_waitcnt lgkmcnt(2)
	v_mov_b32_e32 v224, v153
	s_waitcnt lgkmcnt(1)
	v_mov_b32_e32 v226, v155
	s_waitcnt lgkmcnt(0)
	v_mov_b32_e32 v228, v157
	v_add_u32_e32 v56, 0x80, v56
	s_cmpk_gt_u32 s10, 0x5f
	s_waitcnt vmcnt(7)
	v_pk_fma_f32 v[46:47], v[58:59], v[50:51], v[46:47] op_sel_hi:[1,0,1]
	v_pk_fma_f32 v[44:45], v[60:61], v[50:51], v[44:45] op_sel_hi:[1,0,1]
	v_pk_fma_f32 v[42:43], v[58:59], v[94:95], v[42:43] op_sel_hi:[1,0,1]
	v_pk_fma_f32 v[40:41], v[60:61], v[94:95], v[40:41] op_sel_hi:[1,0,1]
	v_pk_fma_f32 v[38:39], v[58:59], v[96:97], v[38:39] op_sel_hi:[1,0,1]
	v_pk_fma_f32 v[36:37], v[60:61], v[96:97], v[36:37] op_sel_hi:[1,0,1]
	v_pk_fma_f32 v[34:35], v[58:59], v[98:99], v[34:35] op_sel_hi:[1,0,1]
	v_pk_fma_f32 v[30:31], v[60:61], v[98:99], v[30:31] op_sel_hi:[1,0,1]
	v_pk_fma_f32 v[32:33], v[58:59], v[100:101], v[32:33] op_sel_hi:[1,0,1]
	v_pk_fma_f32 v[28:29], v[60:61], v[100:101], v[28:29] op_sel_hi:[1,0,1]
	v_pk_fma_f32 v[26:27], v[58:59], v[102:103], v[26:27] op_sel_hi:[1,0,1]
	v_pk_fma_f32 v[22:23], v[60:61], v[102:103], v[22:23] op_sel_hi:[1,0,1]
	v_pk_fma_f32 v[24:25], v[58:59], v[104:105], v[24:25] op_sel_hi:[1,0,1]
	v_pk_fma_f32 v[18:19], v[60:61], v[104:105], v[18:19] op_sel_hi:[1,0,1]
	v_pk_fma_f32 v[16:17], v[58:59], v[106:107], v[16:17] op_sel_hi:[1,0,1]
	v_pk_fma_f32 v[14:15], v[60:61], v[106:107], v[14:15] op_sel_hi:[1,0,1]
	v_pk_fma_f32 v[12:13], v[58:59], v[108:109], v[12:13] op_sel_hi:[1,0,1]
	v_pk_fma_f32 v[10:11], v[60:61], v[108:109], v[10:11] op_sel_hi:[1,0,1]
	s_waitcnt vmcnt(6)
; __device__ __forceinline__ void p0_mod_item(LAS unsigned char* lds, int item, const float* w_ada, const float* b_ada, float* MOD, int tid) {
;     ...
;         for (int i = 0; i < 8; ++i) { const int k = wave * 128 + k0 + i * 4 + kr;
; #pragma unroll
;             for (int r = 0; r < 9; ++r) acc[r] = acc[r] + wv[i] * sl[r * 1024 + k]; }
	v_pk_fma_f32 v[44:45], v[64:65], v[158:159], v[44:45] op_sel_hi:[1,0,1]
	v_pk_fma_f32 v[46:47], v[62:63], v[158:159], v[46:47] op_sel_hi:[1,0,1]
	v_pk_fma_f32 v[40:41], v[64:65], v[166:167], v[40:41] op_sel_hi:[1,0,1]
	v_pk_fma_f32 v[42:43], v[62:63], v[166:167], v[42:43] op_sel_hi:[1,0,1]
	v_pk_fma_f32 v[36:37], v[64:65], v[168:169], v[36:37] op_sel_hi:[1,0,1]
	v_pk_fma_f32 v[38:39], v[62:63], v[168:169], v[38:39] op_sel_hi:[1,0,1]
	v_pk_fma_f32 v[30:31], v[64:65], v[170:171], v[30:31] op_sel_hi:[1,0,1]
	v_pk_fma_f32 v[34:35], v[62:63], v[170:171], v[34:35] op_sel_hi:[1,0,1]
	v_pk_fma_f32 v[28:29], v[64:65], v[172:173], v[28:29] op_sel_hi:[1,0,1]
	v_pk_fma_f32 v[32:33], v[62:63], v[172:173], v[32:33] op_sel_hi:[1,0,1]
	v_pk_fma_f32 v[22:23], v[64:65], v[174:175], v[22:23] op_sel_hi:[1,0,1]
	v_pk_fma_f32 v[26:27], v[62:63], v[174:175], v[26:27] op_sel_hi:[1,0,1]
	v_pk_fma_f32 v[18:19], v[64:65], v[176:177], v[18:19] op_sel_hi:[1,0,1]
	v_pk_fma_f32 v[24:25], v[62:63], v[176:177], v[24:25] op_sel_hi:[1,0,1]
	v_pk_fma_f32 v[14:15], v[64:65], v[178:179], v[14:15] op_sel_hi:[1,0,1]
	v_pk_fma_f32 v[16:17], v[62:63], v[178:179], v[16:17] op_sel_hi:[1,0,1]
	v_pk_fma_f32 v[10:11], v[64:65], v[180:181], v[10:11] op_sel_hi:[1,0,1]
	v_pk_fma_f32 v[12:13], v[62:63], v[180:181], v[12:13] op_sel_hi:[1,0,1]
	s_waitcnt vmcnt(5)
	v_pk_fma_f32 v[46:47], v[66:67], v[48:49], v[46:47] op_sel_hi:[1,0,1]
	v_pk_fma_f32 v[44:45], v[68:69], v[48:49], v[44:45] op_sel_hi:[1,0,1]
	v_pk_fma_f32 v[42:43], v[66:67], v[110:111], v[42:43] op_sel_hi:[1,0,1]
	v_pk_fma_f32 v[40:41], v[68:69], v[110:111], v[40:41] op_sel_hi:[1,0,1]
	v_pk_fma_f32 v[38:39], v[66:67], v[112:113], v[38:39] op_sel_hi:[1,0,1]
	v_pk_fma_f32 v[36:37], v[68:69], v[112:113], v[36:37] op_sel_hi:[1,0,1]
	v_pk_fma_f32 v[34:35], v[66:67], v[114:115], v[34:35] op_sel_hi:[1,0,1]
	v_pk_fma_f32 v[30:31], v[68:69], v[114:115], v[30:31] op_sel_hi:[1,0,1]
	v_pk_fma_f32 v[32:33], v[66:67], v[116:117], v[32:33] op_sel_hi:[1,0,1]
	v_pk_fma_f32 v[28:29], v[68:69], v[116:117], v[28:29] op_sel_hi:[1,0,1]
	v_pk_fma_f32 v[26:27], v[66:67], v[118:119], v[26:27] op_sel_hi:[1,0,1]
	v_pk_fma_f32 v[22:23], v[68:69], v[118:119], v[22:23] op_sel_hi:[1,0,1]
	v_pk_fma_f32 v[24:25], v[66:67], v[120:121], v[24:25] op_sel_hi:[1,0,1]
	v_pk_fma_f32 v[18:19], v[68:69], v[120:121], v[18:19] op_sel_hi:[1,0,1]
	v_pk_fma_f32 v[16:17], v[66:67], v[122:123], v[16:17] op_sel_hi:[1,0,1]
	v_pk_fma_f32 v[14:15], v[68:69], v[122:123], v[14:15] op_sel_hi:[1,0,1]
	v_pk_fma_f32 v[12:13], v[66:67], v[124:125], v[12:13] op_sel_hi:[1,0,1]
	v_pk_fma_f32 v[10:11], v[68:69], v[124:125], v[10:11] op_sel_hi:[1,0,1]
	s_waitcnt vmcnt(4)
	v_pk_fma_f32 v[44:45], v[72:73], v[160:161], v[44:45] op_sel_hi:[1,0,1]
	v_pk_fma_f32 v[46:47], v[70:71], v[160:161], v[46:47] op_sel_hi:[1,0,1]
	v_pk_fma_f32 v[40:41], v[72:73], v[182:183], v[40:41] op_sel_hi:[1,0,1]
	v_pk_fma_f32 v[42:43], v[70:71], v[182:183], v[42:43] op_sel_hi:[1,0,1]
	v_pk_fma_f32 v[36:37], v[72:73], v[184:185], v[36:37] op_sel_hi:[1,0,1]
	v_pk_fma_f32 v[38:39], v[70:71], v[184:185], v[38:39] op_sel_hi:[1,0,1]
	v_pk_fma_f32 v[30:31], v[72:73], v[186:187], v[30:31] op_sel_hi:[1,0,1]
	v_pk_fma_f32 v[34:35], v[70:71], v[186:187], v[34:35] op_sel_hi:[1,0,1]
	v_pk_fma_f32 v[28:29], v[72:73], v[188:189], v[28:29] op_sel_hi:[1,0,1]
	v_pk_fma_f32 v[32:33], v[70:71], v[188:189], v[32:33] op_sel_hi:[1,0,1]
	v_pk_fma_f32 v[22:23], v[72:73], v[190:191], v[22:23] op_sel_hi:[1,0,1]
	v_pk_fma_f32 v[26:27], v[70:71], v[190:191], v[26:27] op_sel_hi:[1,0,1]
	v_pk_fma_f32 v[18:19], v[72:73], v[192:193], v[18:19] op_sel_hi:[1,0,1]
	v_pk_fma_f32 v[24:25], v[70:71], v[192:193], v[24:25] op_sel_hi:[1,0,1]
	v_pk_fma_f32 v[14:15], v[72:73], v[194:195], v[14:15] op_sel_hi:[1,0,1]
	v_pk_fma_f32 v[16:17], v[70:71], v[194:195], v[16:17] op_sel_hi:[1,0,1]
	v_pk_fma_f32 v[10:11], v[72:73], v[196:197], v[10:11] op_sel_hi:[1,0,1]
	v_pk_fma_f32 v[12:13], v[70:71], v[196:197], v[12:13] op_sel_hi:[1,0,1]
	s_waitcnt vmcnt(3)
	v_pk_fma_f32 v[46:47], v[74:75], v[52:53], v[46:47] op_sel_hi:[1,0,1]
	v_pk_fma_f32 v[44:45], v[76:77], v[52:53], v[44:45] op_sel_hi:[1,0,1]
	v_pk_fma_f32 v[42:43], v[74:75], v[126:127], v[42:43] op_sel_hi:[1,0,1]
	v_pk_fma_f32 v[40:41], v[76:77], v[126:127], v[40:41] op_sel_hi:[1,0,1]
	v_pk_fma_f32 v[38:39], v[74:75], v[128:129], v[38:39] op_sel_hi:[1,0,1]
	v_pk_fma_f32 v[36:37], v[76:77], v[128:129], v[36:37] op_sel_hi:[1,0,1]
	v_pk_fma_f32 v[34:35], v[74:75], v[130:131], v[34:35] op_sel_hi:[1,0,1]
	v_pk_fma_f32 v[30:31], v[76:77], v[130:131], v[30:31] op_sel_hi:[1,0,1]
	v_pk_fma_f32 v[32:33], v[74:75], v[132:133], v[32:33] op_sel_hi:[1,0,1]
	v_pk_fma_f32 v[28:29], v[76:77], v[132:133], v[28:29] op_sel_hi:[1,0,1]
	v_pk_fma_f32 v[26:27], v[74:75], v[134:135], v[26:27] op_sel_hi:[1,0,1]
	v_pk_fma_f32 v[22:23], v[76:77], v[134:135], v[22:23] op_sel_hi:[1,0,1]
	v_pk_fma_f32 v[24:25], v[74:75], v[136:137], v[24:25] op_sel_hi:[1,0,1]
	v_pk_fma_f32 v[18:19], v[76:77], v[136:137], v[18:19] op_sel_hi:[1,0,1]
	v_pk_fma_f32 v[16:17], v[74:75], v[138:139], v[16:17] op_sel_hi:[1,0,1]
	v_pk_fma_f32 v[14:15], v[76:77], v[138:139], v[14:15] op_sel_hi:[1,0,1]
	v_pk_fma_f32 v[12:13], v[74:75], v[140:141], v[12:13] op_sel_hi:[1,0,1]
	v_pk_fma_f32 v[10:11], v[76:77], v[140:141], v[10:11] op_sel_hi:[1,0,1]
	s_waitcnt vmcnt(2)
; __device__ __forceinline__ void p0_mod_item(LAS unsigned char* lds, int item, const float* w_ada, const float* b_ada, float* MOD, int tid) {
;     ...
;         for (int i = 0; i < 8; ++i) { const int k = wave * 128 + k0 + i * 4 + kr;
; #pragma unroll
;             for (int r = 0; r < 9; ++r) acc[r] = acc[r] + wv[i] * sl[r * 1024 + k]; }
;     }
	v_pk_fma_f32 v[44:45], v[80:81], v[162:163], v[44:45] op_sel_hi:[1,0,1]
	v_pk_fma_f32 v[46:47], v[78:79], v[162:163], v[46:47] op_sel_hi:[1,0,1]
	v_pk_fma_f32 v[40:41], v[80:81], v[198:199], v[40:41] op_sel_hi:[1,0,1]
	v_pk_fma_f32 v[42:43], v[78:79], v[198:199], v[42:43] op_sel_hi:[1,0,1]
	v_pk_fma_f32 v[36:37], v[80:81], v[200:201], v[36:37] op_sel_hi:[1,0,1]
	v_pk_fma_f32 v[38:39], v[78:79], v[200:201], v[38:39] op_sel_hi:[1,0,1]
	v_pk_fma_f32 v[30:31], v[80:81], v[202:203], v[30:31] op_sel_hi:[1,0,1]
	v_pk_fma_f32 v[34:35], v[78:79], v[202:203], v[34:35] op_sel_hi:[1,0,1]
	v_pk_fma_f32 v[28:29], v[80:81], v[204:205], v[28:29] op_sel_hi:[1,0,1]
	v_pk_fma_f32 v[32:33], v[78:79], v[204:205], v[32:33] op_sel_hi:[1,0,1]
	v_pk_fma_f32 v[22:23], v[80:81], v[206:207], v[22:23] op_sel_hi:[1,0,1]
	v_pk_fma_f32 v[26:27], v[78:79], v[206:207], v[26:27] op_sel_hi:[1,0,1]
	v_pk_fma_f32 v[18:19], v[80:81], v[208:209], v[18:19] op_sel_hi:[1,0,1]
	v_pk_fma_f32 v[24:25], v[78:79], v[208:209], v[24:25] op_sel_hi:[1,0,1]
	v_pk_fma_f32 v[14:15], v[80:81], v[210:211], v[14:15] op_sel_hi:[1,0,1]
	v_pk_fma_f32 v[16:17], v[78:79], v[210:211], v[16:17] op_sel_hi:[1,0,1]
	v_pk_fma_f32 v[10:11], v[80:81], v[212:213], v[10:11] op_sel_hi:[1,0,1]
	v_pk_fma_f32 v[12:13], v[78:79], v[212:213], v[12:13] op_sel_hi:[1,0,1]
	s_waitcnt vmcnt(1)
	v_pk_fma_f32 v[46:47], v[86:87], v[54:55], v[46:47] op_sel_hi:[1,0,1]
	v_pk_fma_f32 v[44:45], v[88:89], v[54:55], v[44:45] op_sel_hi:[1,0,1]
	v_pk_fma_f32 v[42:43], v[86:87], v[142:143], v[42:43] op_sel_hi:[1,0,1]
	v_pk_fma_f32 v[40:41], v[88:89], v[142:143], v[40:41] op_sel_hi:[1,0,1]
	v_pk_fma_f32 v[38:39], v[86:87], v[144:145], v[38:39] op_sel_hi:[1,0,1]
	v_pk_fma_f32 v[36:37], v[88:89], v[144:145], v[36:37] op_sel_hi:[1,0,1]
	v_pk_fma_f32 v[34:35], v[86:87], v[146:147], v[34:35] op_sel_hi:[1,0,1]
	v_pk_fma_f32 v[30:31], v[88:89], v[146:147], v[30:31] op_sel_hi:[1,0,1]
	v_pk_fma_f32 v[32:33], v[86:87], v[148:149], v[32:33] op_sel_hi:[1,0,1]
	v_pk_fma_f32 v[28:29], v[88:89], v[148:149], v[28:29] op_sel_hi:[1,0,1]
	v_pk_fma_f32 v[26:27], v[86:87], v[150:151], v[26:27] op_sel_hi:[1,0,1]
	v_pk_fma_f32 v[22:23], v[88:89], v[150:151], v[22:23] op_sel_hi:[1,0,1]
	v_pk_fma_f32 v[24:25], v[86:87], v[152:153], v[24:25] op_sel_hi:[1,0,1]
	v_pk_fma_f32 v[18:19], v[88:89], v[152:153], v[18:19] op_sel_hi:[1,0,1]
	v_pk_fma_f32 v[16:17], v[86:87], v[154:155], v[16:17] op_sel_hi:[1,0,1]
	v_pk_fma_f32 v[14:15], v[88:89], v[154:155], v[14:15] op_sel_hi:[1,0,1]
	v_pk_fma_f32 v[12:13], v[86:87], v[156:157], v[12:13] op_sel_hi:[1,0,1]
	v_pk_fma_f32 v[10:11], v[88:89], v[156:157], v[10:11] op_sel_hi:[1,0,1]
	s_waitcnt vmcnt(0)
	v_pk_fma_f32 v[44:45], v[92:93], v[164:165], v[44:45] op_sel_hi:[1,0,1]
	v_pk_fma_f32 v[46:47], v[90:91], v[164:165], v[46:47] op_sel_hi:[1,0,1]
	v_pk_fma_f32 v[40:41], v[92:93], v[214:215], v[40:41] op_sel_hi:[1,0,1]
	v_pk_fma_f32 v[42:43], v[90:91], v[214:215], v[42:43] op_sel_hi:[1,0,1]
	v_pk_fma_f32 v[36:37], v[92:93], v[216:217], v[36:37] op_sel_hi:[1,0,1]
	v_pk_fma_f32 v[38:39], v[90:91], v[216:217], v[38:39] op_sel_hi:[1,0,1]
	v_pk_fma_f32 v[30:31], v[92:93], v[218:219], v[30:31] op_sel_hi:[1,0,1]
	v_pk_fma_f32 v[34:35], v[90:91], v[218:219], v[34:35] op_sel_hi:[1,0,1]
	v_pk_fma_f32 v[28:29], v[92:93], v[220:221], v[28:29] op_sel_hi:[1,0,1]
	v_pk_fma_f32 v[32:33], v[90:91], v[220:221], v[32:33] op_sel_hi:[1,0,1]
	v_pk_fma_f32 v[22:23], v[92:93], v[222:223], v[22:23] op_sel_hi:[1,0,1]
	v_pk_fma_f32 v[26:27], v[90:91], v[222:223], v[26:27] op_sel_hi:[1,0,1]
	v_pk_fma_f32 v[18:19], v[92:93], v[224:225], v[18:19] op_sel_hi:[1,0,1]
	v_pk_fma_f32 v[24:25], v[90:91], v[224:225], v[24:25] op_sel_hi:[1,0,1]
	v_pk_fma_f32 v[14:15], v[92:93], v[226:227], v[14:15] op_sel_hi:[1,0,1]
	v_pk_fma_f32 v[16:17], v[90:91], v[226:227], v[16:17] op_sel_hi:[1,0,1]
	v_pk_fma_f32 v[10:11], v[92:93], v[228:229], v[10:11] op_sel_hi:[1,0,1]
	v_pk_fma_f32 v[12:13], v[90:91], v[228:229], v[12:13] op_sel_hi:[1,0,1]
	s_cbranch_scc0 .LBB0_14
; __device__ __forceinline__ void p0_mod_item(LAS unsigned char* lds, int item, const float* w_ada, const float* b_ada, float* MOD, int tid) {
;     ...
; #pragma unroll
;     for (int r = 0; r < 9; ++r)
; #pragma unroll
;         for (int e = 0; e < 4; ++e) { float v = acc[r][e]; v += __shfl_xor(v, 16); v += __shfl_xor(v, 32); acc[r][e] = v; }
;     if (kr == 0) {
; #pragma unroll
;         for (int r = 0; r < 9; ++r)
; #pragma unroll
;             for (int e = 0; e < 4; ++e) red[(wave * 9 + r) * 64 + c4 * 4 + e] = acc[r][e];
;     }
	ds_bpermute_b32 v60, v7, v34
	ds_bpermute_b32 v61, v7, v35
	ds_bpermute_b32 v64, v7, v32
	ds_bpermute_b32 v65, v7, v33
	ds_bpermute_b32 v66, v7, v28
	ds_bpermute_b32 v67, v7, v29
	s_waitcnt lgkmcnt(4)
	v_pk_add_f32 v[34:35], v[34:35], v[60:61]
	ds_bpermute_b32 v60, v7, v30
	ds_bpermute_b32 v61, v7, v31
	ds_bpermute_b32 v20, v7, v46
	s_waitcnt lgkmcnt(3)
	v_pk_add_f32 v[28:29], v[28:29], v[66:67]
	ds_bpermute_b32 v66, v7, v24
	ds_bpermute_b32 v67, v7, v25
	s_waitcnt lgkmcnt(3)
	v_pk_add_f32 v[60:61], v[30:31], v[60:61]
	v_pk_add_f32 v[30:31], v[32:33], v[64:65]
	ds_bpermute_b32 v32, v7, v26
	ds_bpermute_b32 v33, v7, v27
	ds_bpermute_b32 v64, v7, v22
	ds_bpermute_b32 v65, v7, v23
	ds_bpermute_b32 v21, v7, v47
	ds_bpermute_b32 v48, v7, v44
	s_waitcnt lgkmcnt(4)
	v_pk_add_f32 v[26:27], v[26:27], v[32:33]
	ds_bpermute_b32 v49, v7, v45
	s_waitcnt lgkmcnt(3)
	v_pk_add_f32 v[32:33], v[22:23], v[64:65]
	v_pk_add_f32 v[22:23], v[24:25], v[66:67]
	ds_bpermute_b32 v64, v7, v16
	ds_bpermute_b32 v65, v7, v17
	ds_bpermute_b32 v66, v7, v14
	ds_bpermute_b32 v67, v7, v15
	ds_bpermute_b32 v50, v7, v42
	ds_bpermute_b32 v51, v7, v43
	ds_bpermute_b32 v52, v7, v40
	ds_bpermute_b32 v53, v7, v41
	ds_bpermute_b32 v54, v7, v38
	ds_bpermute_b32 v55, v7, v39
	ds_bpermute_b32 v56, v7, v36
	ds_bpermute_b32 v57, v7, v37
	ds_bpermute_b32 v68, v7, v18
	ds_bpermute_b32 v69, v7, v19
	s_waitcnt lgkmcnt(12)
	v_pk_add_f32 v[16:17], v[16:17], v[64:65]
	ds_bpermute_b32 v64, v7, v12
	ds_bpermute_b32 v65, v7, v13
	s_waitcnt lgkmcnt(12)
	v_pk_add_f32 v[14:15], v[14:15], v[66:67]
	ds_bpermute_b32 v66, v7, v10
	ds_bpermute_b32 v67, v7, v11
	v_pk_add_f32 v[20:21], v[46:47], v[20:21]
	v_pk_add_f32 v[44:45], v[44:45], v[48:49]
	s_waitcnt lgkmcnt(12)
	v_pk_add_f32 v[42:43], v[42:43], v[50:51]
	s_waitcnt lgkmcnt(10)
	v_pk_add_f32 v[40:41], v[40:41], v[52:53]
	s_waitcnt lgkmcnt(8)
	v_pk_add_f32 v[38:39], v[38:39], v[54:55]
	s_waitcnt lgkmcnt(6)
	v_pk_add_f32 v[36:37], v[36:37], v[56:57]
	s_waitcnt lgkmcnt(4)
	v_pk_add_f32 v[18:19], v[18:19], v[68:69]
	s_waitcnt lgkmcnt(2)
	v_pk_add_f32 v[12:13], v[12:13], v[64:65]
	s_waitcnt lgkmcnt(0)
	v_pk_add_f32 v[10:11], v[10:11], v[66:67]
	ds_bpermute_b32 v46, v82, v20
	ds_bpermute_b32 v47, v82, v21
	ds_bpermute_b32 v48, v82, v44
	ds_bpermute_b32 v49, v82, v45
	ds_bpermute_b32 v50, v82, v42
	ds_bpermute_b32 v51, v82, v43
	ds_bpermute_b32 v52, v82, v40
	ds_bpermute_b32 v53, v82, v41
	ds_bpermute_b32 v54, v82, v38
	ds_bpermute_b32 v55, v82, v39
	ds_bpermute_b32 v58, v82, v36
	ds_bpermute_b32 v59, v82, v37
	ds_bpermute_b32 v56, v82, v34
	ds_bpermute_b32 v57, v82, v35
	ds_bpermute_b32 v62, v82, v60
	ds_bpermute_b32 v63, v82, v61
	ds_bpermute_b32 v24, v82, v30
	ds_bpermute_b32 v25, v82, v31
	ds_bpermute_b32 v76, v82, v28
	ds_bpermute_b32 v77, v82, v29
	ds_bpermute_b32 v78, v82, v26
	ds_bpermute_b32 v79, v82, v27
	ds_bpermute_b32 v80, v82, v32
	ds_bpermute_b32 v81, v82, v33
	ds_bpermute_b32 v72, v82, v22
	ds_bpermute_b32 v73, v82, v23
	ds_bpermute_b32 v74, v82, v18
	ds_bpermute_b32 v75, v82, v19
	ds_bpermute_b32 v68, v82, v16
	ds_bpermute_b32 v69, v82, v17
	ds_bpermute_b32 v70, v82, v14
	ds_bpermute_b32 v71, v82, v15
	ds_bpermute_b32 v64, v82, v12
	ds_bpermute_b32 v65, v82, v13
	ds_bpermute_b32 v66, v82, v10
	ds_bpermute_b32 v67, v82, v11
	s_and_saveexec_b64 s[10:11], vcc
	s_cbranch_execz .LBB0_17
	s_waitcnt lgkmcnt(14)
	v_pk_add_f32 v[48:49], v[44:45], v[48:49]
	v_pk_add_f32 v[44:45], v[40:41], v[52:53]
	v_pk_add_f32 v[40:41], v[36:37], v[58:59]
	v_pk_add_f32 v[34:35], v[34:35], v[56:57]
	v_pk_add_f32 v[36:37], v[60:61], v[62:63]
	v_pk_add_f32 v[46:47], v[20:21], v[46:47]
	v_pk_add_f32 v[42:43], v[42:43], v[50:51]
	v_pk_add_f32 v[38:39], v[38:39], v[54:55]
	ds_write_b128 v85, v[34:37] offset:37632
	v_pk_add_f32 v[34:35], v[30:31], v[24:25]
	v_pk_add_f32 v[36:37], v[28:29], v[76:77]
	v_pk_add_f32 v[24:25], v[26:27], v[78:79]
	s_waitcnt lgkmcnt(13)
	v_pk_add_f32 v[26:27], v[32:33], v[80:81]
	s_waitcnt lgkmcnt(11)
	v_pk_add_f32 v[20:21], v[22:23], v[72:73]
	s_waitcnt lgkmcnt(9)
	v_pk_add_f32 v[22:23], v[18:19], v[74:75]
	s_waitcnt lgkmcnt(7)
	v_pk_add_f32 v[16:17], v[16:17], v[68:69]
	s_waitcnt lgkmcnt(5)
	v_pk_add_f32 v[18:19], v[14:15], v[70:71]
	s_waitcnt lgkmcnt(3)
	v_pk_add_f32 v[12:13], v[12:13], v[64:65]
	s_waitcnt lgkmcnt(1)
	v_pk_add_f32 v[14:15], v[10:11], v[66:67]
	ds_write_b128 v85, v[46:49] offset:36864
	ds_write_b128 v85, v[42:45] offset:37120
	ds_write_b128 v85, v[38:41] offset:37376
	ds_write_b128 v85, v[34:37] offset:37888
	ds_write_b128 v85, v[24:27] offset:38144
	ds_write_b128 v85, v[20:23] offset:38400
	ds_write_b128 v85, v[16:19] offset:38656
	ds_write_b128 v85, v[12:15] offset:38912
